# P6 epilogue: residual loads of 3 row groups in flight (was one dependent load/wait/store round trip per 16 B)
# speedup vs baseline: 1.1163x; 1.0084x over previous
;     __device__ __forceinline__ void operator()(const f32x4 (&acc)[2][2][4][2], const pg8::Unit& u, int wr, int wc, int fr, int fq) const {
;     ...
;         for (int ai = 0; ai < 2; ++ai)
; #pragma unroll
;             for (int m = 0; m < 4; ++m) { const size_t off = (size_t)(row0 + ai * 128 + m * 16) * ldc + col0;
; #pragma unroll
;                 for (int bj = 0; bj < 2; ++bj)
; #pragma unroll
;                     for (int n = 0; n < 2; ++n) { const f32x4 b = *(const f32x4*)(base + off + bj * 128 + n * 16); *(f32x4*)(out + off + bj * 128 + n * 16) = b + gv[bj][n] * acc[ai][bj][m][n]; }
;                 asm volatile("" ::: "memory"); }
.LBB0_656:
	s_ashr_i32 s11, s16, 31
	v_lshl_add_u32 v172, s16, 8, v174
	v_lshl_or_b32 v170, s17, 8, v176
	s_lshr_b32 s11, s11, 29
	v_ashrrev_i32_e32 v173, 31, v172
	s_add_i32 s11, s16, s11
	v_ashrrev_i32_e32 v171, 31, v170
	v_lshlrev_b64 v[168:169], 11, v[172:173]
	s_ashr_i32 s11, s11, 3
	v_lshl_add_u64 v[168:169], v[168:169], 0, v[170:171]
	v_mad_i64_i32 v[120:121], s[18:19], s11, v193, v[158:159]
	v_lshlrev_b64 v[168:169], 2, v[168:169]
	v_lshl_add_u64 v[120:121], v[170:171], 2, v[120:121]
	s_waitcnt vmcnt(0)
	v_lshl_add_u64 v[170:171], v[146:147], 0, v[168:169]
	v_lshl_add_u64 v[172:173], v[144:145], 0, v[168:169]
	global_load_dwordx4 v[136:139], v[120:121], off
	global_load_dwordx4 v[132:135], v[120:121], off offset:64
	global_load_dwordx4 v[128:131], v[120:121], off offset:512
	s_nop 0
	global_load_dwordx4 v[120:123], v[120:121], off offset:576
	s_mov_b64 s[16:17], 0x0
	v_lshl_add_u64 v[178:179], v[170:171], 0, s[16:17]
	global_load_dwordx4 v[200:203], v[178:179], off
	global_load_dwordx4 v[204:207], v[178:179], off offset:64
	global_load_dwordx4 v[208:211], v[178:179], off offset:512
	global_load_dwordx4 v[212:215], v[178:179], off offset:576
	s_mov_b64 s[16:17], 0x20000
	v_lshl_add_u64 v[178:179], v[170:171], 0, s[16:17]
	global_load_dwordx4 v[216:219], v[178:179], off
	global_load_dwordx4 v[220:223], v[178:179], off offset:64
	global_load_dwordx4 v[224:227], v[178:179], off offset:512
	global_load_dwordx4 v[228:231], v[178:179], off offset:576
	s_mov_b64 s[16:17], 0x40000
	v_lshl_add_u64 v[178:179], v[170:171], 0, s[16:17]
	global_load_dwordx4 v[232:235], v[178:179], off
	global_load_dwordx4 v[236:239], v[178:179], off offset:64
	global_load_dwordx4 v[182:185], v[178:179], off offset:512
	global_load_dwordx4 v[186:189], v[178:179], off offset:576
	s_waitcnt vmcnt(8)
	s_mov_b64 s[16:17], 0x0
	v_lshl_add_u64 v[180:181], v[172:173], 0, s[16:17]
	v_pk_fma_f32 v[142:143], v[142:143], v[138:139], v[202:203]
	v_pk_fma_f32 v[140:141], v[140:141], v[136:137], v[200:201]
	v_pk_fma_f32 v[126:127], v[126:127], v[134:135], v[206:207]
	v_pk_fma_f32 v[124:125], v[124:125], v[132:133], v[204:205]
	v_pk_fma_f32 v[118:119], v[118:119], v[130:131], v[210:211]
	v_pk_fma_f32 v[116:117], v[116:117], v[128:129], v[208:209]
	v_pk_fma_f32 v[114:115], v[114:115], v[122:123], v[214:215]
	v_pk_fma_f32 v[112:113], v[112:113], v[120:121], v[212:213]
	global_store_dwordx4 v[180:181], v[140:143], off
	global_store_dwordx4 v[180:181], v[124:127], off offset:64
	global_store_dwordx4 v[180:181], v[116:119], off offset:512
	global_store_dwordx4 v[180:181], v[112:115], off offset:576
	s_mov_b64 s[16:17], 0x60000
	v_lshl_add_u64 v[178:179], v[170:171], 0, s[16:17]
	global_load_dwordx4 v[200:203], v[178:179], off
	global_load_dwordx4 v[204:207], v[178:179], off offset:64
	global_load_dwordx4 v[208:211], v[178:179], off offset:512
	global_load_dwordx4 v[212:215], v[178:179], off offset:576
	s_waitcnt vmcnt(12)
	s_mov_b64 s[16:17], 0x20000
	v_lshl_add_u64 v[180:181], v[172:173], 0, s[16:17]
	v_pk_fma_f32 v[110:111], v[110:111], v[138:139], v[218:219]
	v_pk_fma_f32 v[108:109], v[108:109], v[136:137], v[216:217]
	v_pk_fma_f32 v[106:107], v[106:107], v[134:135], v[222:223]
	v_pk_fma_f32 v[104:105], v[104:105], v[132:133], v[220:221]
	v_pk_fma_f32 v[102:103], v[102:103], v[130:131], v[226:227]
	v_pk_fma_f32 v[100:101], v[100:101], v[128:129], v[224:225]
	v_pk_fma_f32 v[98:99], v[98:99], v[122:123], v[230:231]
	v_pk_fma_f32 v[96:97], v[96:97], v[120:121], v[228:229]
	global_store_dwordx4 v[180:181], v[108:111], off
	global_store_dwordx4 v[180:181], v[104:107], off offset:64
	global_store_dwordx4 v[180:181], v[100:103], off offset:512
	global_store_dwordx4 v[180:181], v[96:99], off offset:576
	s_mov_b64 s[16:17], 0x100000
	v_lshl_add_u64 v[178:179], v[170:171], 0, s[16:17]
	global_load_dwordx4 v[216:219], v[178:179], off
	global_load_dwordx4 v[220:223], v[178:179], off offset:64
	global_load_dwordx4 v[224:227], v[178:179], off offset:512
	global_load_dwordx4 v[228:231], v[178:179], off offset:576
	s_waitcnt vmcnt(16)
	s_mov_b64 s[16:17], 0x40000
	v_lshl_add_u64 v[180:181], v[172:173], 0, s[16:17]
	v_pk_fma_f32 v[94:95], v[94:95], v[138:139], v[234:235]
	v_pk_fma_f32 v[92:93], v[92:93], v[136:137], v[232:233]
	v_pk_fma_f32 v[90:91], v[90:91], v[134:135], v[238:239]
	v_pk_fma_f32 v[88:89], v[88:89], v[132:133], v[236:237]
	v_pk_fma_f32 v[86:87], v[86:87], v[130:131], v[184:185]
	v_pk_fma_f32 v[84:85], v[84:85], v[128:129], v[182:183]
	v_pk_fma_f32 v[82:83], v[82:83], v[122:123], v[188:189]
	v_pk_fma_f32 v[80:81], v[80:81], v[120:121], v[186:187]
	global_store_dwordx4 v[180:181], v[92:95], off
	global_store_dwordx4 v[180:181], v[88:91], off offset:64
	global_store_dwordx4 v[180:181], v[84:87], off offset:512
	global_store_dwordx4 v[180:181], v[80:83], off offset:576
	s_mov_b64 s[16:17], 0x120000
	v_lshl_add_u64 v[178:179], v[170:171], 0, s[16:17]
	global_load_dwordx4 v[232:235], v[178:179], off
	global_load_dwordx4 v[236:239], v[178:179], off offset:64
	global_load_dwordx4 v[182:185], v[178:179], off offset:512
	global_load_dwordx4 v[186:189], v[178:179], off offset:576
	s_waitcnt vmcnt(16)
;     __device__ __forceinline__ void operator()(const f32x4 (&acc)[2][2][4][2], const pg8::Unit& u, int wr, int wc, int fr, int fq) const {
;     ...
;         for (int ai = 0; ai < 2; ++ai)
; #pragma unroll
;             for (int m = 0; m < 4; ++m) { const size_t off = (size_t)(row0 + ai * 128 + m * 16) * ldc + col0;
; #pragma unroll
;                 for (int bj = 0; bj < 2; ++bj)
; #pragma unroll
;                     for (int n = 0; n < 2; ++n) { const f32x4 b = *(const f32x4*)(base + off + bj * 128 + n * 16); *(f32x4*)(out + off + bj * 128 + n * 16) = b + gv[bj][n] * acc[ai][bj][m][n]; }
;                 asm volatile("" ::: "memory"); }
	s_mov_b64 s[16:17], 0x60000
	v_lshl_add_u64 v[180:181], v[172:173], 0, s[16:17]
	v_pk_fma_f32 v[78:79], v[78:79], v[138:139], v[202:203]
	v_pk_fma_f32 v[76:77], v[76:77], v[136:137], v[200:201]
	v_pk_fma_f32 v[74:75], v[74:75], v[134:135], v[206:207]
	v_pk_fma_f32 v[72:73], v[72:73], v[132:133], v[204:205]
	v_pk_fma_f32 v[70:71], v[70:71], v[130:131], v[210:211]
	v_pk_fma_f32 v[68:69], v[68:69], v[128:129], v[208:209]
	v_pk_fma_f32 v[66:67], v[66:67], v[122:123], v[214:215]
	v_pk_fma_f32 v[64:65], v[64:65], v[120:121], v[212:213]
	global_store_dwordx4 v[180:181], v[76:79], off
	global_store_dwordx4 v[180:181], v[72:75], off offset:64
	global_store_dwordx4 v[180:181], v[68:71], off offset:512
	global_store_dwordx4 v[180:181], v[64:67], off offset:576
	s_mov_b64 s[16:17], 0x140000
	v_lshl_add_u64 v[178:179], v[170:171], 0, s[16:17]
	global_load_dwordx4 v[200:203], v[178:179], off
	global_load_dwordx4 v[204:207], v[178:179], off offset:64
	global_load_dwordx4 v[208:211], v[178:179], off offset:512
	global_load_dwordx4 v[212:215], v[178:179], off offset:576
	s_waitcnt vmcnt(16)
	s_mov_b64 s[16:17], 0x100000
	v_lshl_add_u64 v[180:181], v[172:173], 0, s[16:17]
	v_pk_fma_f32 v[62:63], v[62:63], v[138:139], v[218:219]
	v_pk_fma_f32 v[60:61], v[60:61], v[136:137], v[216:217]
	v_pk_fma_f32 v[58:59], v[58:59], v[134:135], v[222:223]
	v_pk_fma_f32 v[56:57], v[56:57], v[132:133], v[220:221]
	v_pk_fma_f32 v[54:55], v[54:55], v[130:131], v[226:227]
	v_pk_fma_f32 v[52:53], v[52:53], v[128:129], v[224:225]
	v_pk_fma_f32 v[50:51], v[50:51], v[122:123], v[230:231]
	v_pk_fma_f32 v[48:49], v[48:49], v[120:121], v[228:229]
	global_store_dwordx4 v[180:181], v[60:63], off
	global_store_dwordx4 v[180:181], v[56:59], off offset:64
	global_store_dwordx4 v[180:181], v[52:55], off offset:512
	global_store_dwordx4 v[180:181], v[48:51], off offset:576
	s_mov_b64 s[16:17], 0x160000
	v_lshl_add_u64 v[178:179], v[170:171], 0, s[16:17]
	global_load_dwordx4 v[216:219], v[178:179], off
	global_load_dwordx4 v[220:223], v[178:179], off offset:64
	global_load_dwordx4 v[224:227], v[178:179], off offset:512
	global_load_dwordx4 v[228:231], v[178:179], off offset:576
	s_waitcnt vmcnt(16)
	s_mov_b64 s[16:17], 0x120000
	v_lshl_add_u64 v[180:181], v[172:173], 0, s[16:17]
	v_pk_fma_f32 v[46:47], v[46:47], v[138:139], v[234:235]
	v_pk_fma_f32 v[44:45], v[44:45], v[136:137], v[232:233]
	v_pk_fma_f32 v[42:43], v[42:43], v[134:135], v[238:239]
	v_pk_fma_f32 v[40:41], v[40:41], v[132:133], v[236:237]
	v_pk_fma_f32 v[38:39], v[38:39], v[130:131], v[184:185]
	v_pk_fma_f32 v[36:37], v[36:37], v[128:129], v[182:183]
	v_pk_fma_f32 v[34:35], v[34:35], v[122:123], v[188:189]
	v_pk_fma_f32 v[32:33], v[32:33], v[120:121], v[186:187]
	global_store_dwordx4 v[180:181], v[44:47], off
	global_store_dwordx4 v[180:181], v[40:43], off offset:64
	global_store_dwordx4 v[180:181], v[36:39], off offset:512
	global_store_dwordx4 v[180:181], v[32:35], off offset:576
	s_waitcnt vmcnt(12)
	s_mov_b64 s[16:17], 0x140000
	v_lshl_add_u64 v[180:181], v[172:173], 0, s[16:17]
	v_pk_fma_f32 v[30:31], v[30:31], v[138:139], v[202:203]
	v_pk_fma_f32 v[28:29], v[28:29], v[136:137], v[200:201]
	v_pk_fma_f32 v[26:27], v[26:27], v[134:135], v[206:207]
	v_pk_fma_f32 v[24:25], v[24:25], v[132:133], v[204:205]
	v_pk_fma_f32 v[22:23], v[22:23], v[130:131], v[210:211]
	v_pk_fma_f32 v[20:21], v[20:21], v[128:129], v[208:209]
	v_pk_fma_f32 v[18:19], v[18:19], v[122:123], v[214:215]
	v_pk_fma_f32 v[16:17], v[16:17], v[120:121], v[212:213]
	global_store_dwordx4 v[180:181], v[28:31], off
	global_store_dwordx4 v[180:181], v[24:27], off offset:64
	global_store_dwordx4 v[180:181], v[20:23], off offset:512
	global_store_dwordx4 v[180:181], v[16:19], off offset:576
	s_waitcnt vmcnt(8)
	s_mov_b64 s[16:17], 0x160000
	v_lshl_add_u64 v[180:181], v[172:173], 0, s[16:17]
	v_pk_fma_f32 v[14:15], v[14:15], v[138:139], v[218:219]
	v_pk_fma_f32 v[12:13], v[12:13], v[136:137], v[216:217]
	v_pk_fma_f32 v[10:11], v[10:11], v[134:135], v[222:223]
	v_pk_fma_f32 v[8:9], v[8:9], v[132:133], v[220:221]
	v_pk_fma_f32 v[6:7], v[6:7], v[130:131], v[226:227]
	v_pk_fma_f32 v[4:5], v[4:5], v[128:129], v[224:225]
	v_pk_fma_f32 v[2:3], v[2:3], v[122:123], v[230:231]
	v_pk_fma_f32 v[0:1], v[0:1], v[120:121], v[228:229]
	global_store_dwordx4 v[180:181], v[12:15], off
	global_store_dwordx4 v[180:181], v[8:11], off offset:64
	global_store_dwordx4 v[180:181], v[4:7], off offset:512
	global_store_dwordx4 v[180:181], v[0:3], off offset:576
	s_mov_b64 s[16:17], -1
	s_andn2_b64 vcc, exec, s[4:5]
	s_cbranch_vccnz .LBB0_645
	s_andn2_b64 vcc, exec, s[6:7]
	s_cbranch_vccnz .LBB0_644
	s_barrier
	s_branch .LBB0_644
